# MLA epilogue: gate loads and OG stores as 16-byte row-contiguous accesses via a per-wave LDS transpose (was 2-byte per lane)
# speedup vs baseline: 1.0012x; 1.0012x over previous
.LBB0_299:
	s_or_b64 exec, exec, s[10:11]
	s_mul_i32 s8, s90, s71
	s_mul_hi_u32 s9, s90, s71
	s_mul_i32 s12, s91, s71
	s_add_u32 s9, s9, s12
	s_add_u32 s10, s80, s8
	s_addc_u32 s11, s81, s9
	s_lshl_b64 s[12:13], s[90:91], 12
	s_add_u32 s12, s12, s78
	s_addc_u32 s13, s13, s79
	s_lshl_b32 s8, s71, 2
	v_readlane_b32 s9, v255, 2
	v_lshrrev_b32_e32 v68, 5, v67
	v_lshrrev_b32_e32 v69, 4, v67
	v_and_b32_e32 v70, 15, v67
	s_mul_i32 s9, s9, 0x2200
	v_lshl_add_u32 v71, v68, 4, s93
	v_lshlrev_b32_e32 v70, 4, v70
	v_mul_lo_u32 v72, v69, s71
	v_lshl_add_u32 v73, v69, 12, v70
	v_add_u32_e32 v72, v72, v70
	s_lshl_b32 s74, s74, 1
	v_mul_u32_u24_e32 v74, 0x440, v68
	v_mul_u32_u24_e32 v75, 0x110, v69
	v_add_u32_e32 v72, s74, v72
	v_add_u32_e32 v73, s74, v73
	s_lshr_b32 s74, s74, 1
	v_lshl_add_u32 v74, v66, 1, v74
	v_add_u32_e32 v75, v75, v70
	v_add_u32_e32 v74, s9, v74
	v_add_u32_e32 v75, s9, v75
	global_load_dwordx4 v[82:85], v72, s[10:11]
	v_add_u32_e32 v72, s8, v72
	global_load_dwordx4 v[86:89], v72, s[10:11]
	v_add_u32_e32 v72, s8, v72
	global_load_dwordx4 v[90:93], v72, s[10:11]
	v_add_u32_e32 v72, s8, v72
	global_load_dwordx4 v[94:97], v72, s[10:11]
	v_add_u32_e32 v72, s8, v72
	global_load_dwordx4 v[98:101], v72, s[10:11]
	v_add_u32_e32 v72, s8, v72
	global_load_dwordx4 v[102:105], v72, s[10:11]
	v_add_u32_e32 v72, s8, v72
	global_load_dwordx4 v[106:109], v72, s[10:11]
	v_add_u32_e32 v72, s8, v72
	global_load_dwordx4 v[110:113], v72, s[10:11]
	s_waitcnt lgkmcnt(0)
	ds_read_b128 v[212:215], v71
	ds_read_b128 v[216:219], v71 offset:32
	ds_read_b128 v[220:223], v71 offset:64
	ds_read_b128 v[224:227], v71 offset:96
	s_waitcnt lgkmcnt(0)
	v_rcp_f32_e32 v212, v212
	v_rcp_f32_e32 v213, v213
	v_rcp_f32_e32 v214, v214
	v_rcp_f32_e32 v215, v215
	v_rcp_f32_e32 v216, v216
	v_rcp_f32_e32 v217, v217
	v_rcp_f32_e32 v218, v218
	v_rcp_f32_e32 v219, v219
	v_rcp_f32_e32 v220, v220
	v_rcp_f32_e32 v221, v221
	v_rcp_f32_e32 v222, v222
	v_rcp_f32_e32 v223, v223
	v_rcp_f32_e32 v224, v224
	v_rcp_f32_e32 v225, v225
	v_rcp_f32_e32 v226, v226
	v_rcp_f32_e32 v227, v227
	v_mul_f32_e32 v50, v50, v212
	v_mul_f32_e32 v34, v34, v212
	v_mul_f32_e32 v18, v18, v212
	v_mul_f32_e32 v2, v2, v212
	v_mul_f32_e32 v51, v51, v213
	v_mul_f32_e32 v35, v35, v213
	v_mul_f32_e32 v19, v19, v213
	v_mul_f32_e32 v3, v3, v213
	v_mul_f32_e32 v52, v52, v214
	v_mul_f32_e32 v36, v36, v214
	v_mul_f32_e32 v20, v20, v214
	v_mul_f32_e32 v4, v4, v214
	v_mul_f32_e32 v53, v53, v215
	v_mul_f32_e32 v37, v37, v215
	v_mul_f32_e32 v21, v21, v215
	v_mul_f32_e32 v5, v5, v215
	v_mul_f32_e32 v54, v54, v216
	v_mul_f32_e32 v38, v38, v216
	v_mul_f32_e32 v22, v22, v216
	v_mul_f32_e32 v6, v6, v216
	v_mul_f32_e32 v55, v55, v217
	v_mul_f32_e32 v39, v39, v217
	v_mul_f32_e32 v23, v23, v217
	v_mul_f32_e32 v7, v7, v217
	v_mul_f32_e32 v56, v56, v218
	v_mul_f32_e32 v40, v40, v218
	v_mul_f32_e32 v24, v24, v218
	v_mul_f32_e32 v8, v8, v218
	v_mul_f32_e32 v57, v57, v219
	v_mul_f32_e32 v41, v41, v219
	v_mul_f32_e32 v25, v25, v219
	v_mul_f32_e32 v9, v9, v219
	v_mul_f32_e32 v58, v58, v220
	v_mul_f32_e32 v42, v42, v220
	v_mul_f32_e32 v26, v26, v220
	v_mul_f32_e32 v10, v10, v220
	v_mul_f32_e32 v59, v59, v221
	v_mul_f32_e32 v43, v43, v221
	v_mul_f32_e32 v27, v27, v221
	v_mul_f32_e32 v11, v11, v221
	v_mul_f32_e32 v60, v60, v222
	v_mul_f32_e32 v44, v44, v222
	v_mul_f32_e32 v28, v28, v222
	v_mul_f32_e32 v12, v12, v222
	v_mul_f32_e32 v61, v61, v223
	v_mul_f32_e32 v45, v45, v223
	v_mul_f32_e32 v29, v29, v223
	v_mul_f32_e32 v13, v13, v223
	v_mul_f32_e32 v62, v62, v224
	v_mul_f32_e32 v46, v46, v224
	v_mul_f32_e32 v30, v30, v224
	v_mul_f32_e32 v14, v14, v224
	v_mul_f32_e32 v63, v63, v225
	v_mul_f32_e32 v47, v47, v225
	v_mul_f32_e32 v31, v31, v225
	v_mul_f32_e32 v15, v15, v225
	v_mul_f32_e32 v64, v64, v226
	v_mul_f32_e32 v48, v48, v226
	v_mul_f32_e32 v32, v32, v226
	v_mul_f32_e32 v16, v16, v226
	v_mul_f32_e32 v65, v65, v227
	v_mul_f32_e32 v49, v49, v227
	v_mul_f32_e32 v33, v33, v227
	v_mul_f32_e32 v17, v17, v227
	s_waitcnt vmcnt(0)
	ds_write_b128 v75, v[82:85]
	ds_write_b128 v75, v[86:89] offset:1088
	ds_write_b128 v75, v[90:93] offset:2176
	ds_write_b128 v75, v[94:97] offset:3264
	ds_write_b128 v75, v[98:101] offset:4352
	ds_write_b128 v75, v[102:105] offset:5440
	ds_write_b128 v75, v[106:109] offset:6528
	ds_write_b128 v75, v[110:113] offset:7616
	s_waitcnt lgkmcnt(0)
	ds_read_u16 v82, v74
	ds_read_u16 v83, v74 offset:64
	ds_read_u16 v84, v74 offset:128
	ds_read_u16 v85, v74 offset:192
	ds_read_u16 v86, v74 offset:272
	ds_read_u16 v87, v74 offset:336
	ds_read_u16 v88, v74 offset:400
	ds_read_u16 v89, v74 offset:464
	ds_read_u16 v90, v74 offset:544
	ds_read_u16 v91, v74 offset:608
	ds_read_u16 v92, v74 offset:672
	ds_read_u16 v93, v74 offset:736
	ds_read_u16 v94, v74 offset:816
	ds_read_u16 v95, v74 offset:880
	ds_read_u16 v96, v74 offset:944
	ds_read_u16 v97, v74 offset:1008
	ds_read_u16 v98, v74 offset:2176
	ds_read_u16 v99, v74 offset:2240
	ds_read_u16 v100, v74 offset:2304
	ds_read_u16 v101, v74 offset:2368
	ds_read_u16 v102, v74 offset:2448
	ds_read_u16 v103, v74 offset:2512
	ds_read_u16 v104, v74 offset:2576
	ds_read_u16 v105, v74 offset:2640
	ds_read_u16 v106, v74 offset:2720
	ds_read_u16 v107, v74 offset:2784
	ds_read_u16 v108, v74 offset:2848
	ds_read_u16 v109, v74 offset:2912
	ds_read_u16 v110, v74 offset:2992
	ds_read_u16 v111, v74 offset:3056
	ds_read_u16 v112, v74 offset:3120
	ds_read_u16 v113, v74 offset:3184
	ds_read_u16 v114, v74 offset:4352
	ds_read_u16 v115, v74 offset:4416
	ds_read_u16 v116, v74 offset:4480
	ds_read_u16 v117, v74 offset:4544
	ds_read_u16 v118, v74 offset:4624
	ds_read_u16 v119, v74 offset:4688
	ds_read_u16 v120, v74 offset:4752
	ds_read_u16 v121, v74 offset:4816
	ds_read_u16 v122, v74 offset:4896
	ds_read_u16 v123, v74 offset:4960
	ds_read_u16 v124, v74 offset:5024
	ds_read_u16 v125, v74 offset:5088
	ds_read_u16 v126, v74 offset:5168
	ds_read_u16 v127, v74 offset:5232
	ds_read_u16 v128, v74 offset:5296
	ds_read_u16 v129, v74 offset:5360
	ds_read_u16 v130, v74 offset:6528
	ds_read_u16 v131, v74 offset:6592
	ds_read_u16 v132, v74 offset:6656
	ds_read_u16 v133, v74 offset:6720
	ds_read_u16 v134, v74 offset:6800
	ds_read_u16 v135, v74 offset:6864
	ds_read_u16 v136, v74 offset:6928
	ds_read_u16 v137, v74 offset:6992
	ds_read_u16 v138, v74 offset:7072
	ds_read_u16 v139, v74 offset:7136
	ds_read_u16 v140, v74 offset:7200
	ds_read_u16 v141, v74 offset:7264
	ds_read_u16 v142, v74 offset:7344
	ds_read_u16 v143, v74 offset:7408
	ds_read_u16 v144, v74 offset:7472
	ds_read_u16 v145, v74 offset:7536
	s_waitcnt lgkmcnt(0)
	v_lshlrev_b32_e32 v82, 16, v82
	v_lshlrev_b32_e32 v83, 16, v83
	v_lshlrev_b32_e32 v84, 16, v84
	v_lshlrev_b32_e32 v85, 16, v85
	v_mul_f32_e32 v76, 0xbfb8aa3b, v82
	v_mul_f32_e32 v77, 0xbfb8aa3b, v83
	v_mul_f32_e32 v78, 0xbfb8aa3b, v84
	v_mul_f32_e32 v148, 0xbfb8aa3b, v85
	v_exp_f32_e32 v76, v76
	v_exp_f32_e32 v77, v77
	v_exp_f32_e32 v78, v78
	v_exp_f32_e32 v148, v148
	v_add_f32_e32 v76, 1.0, v76
	v_add_f32_e32 v77, 1.0, v77
	v_add_f32_e32 v78, 1.0, v78
	v_add_f32_e32 v148, 1.0, v148
	v_rcp_f32_e32 v76, v76
	v_rcp_f32_e32 v77, v77
	v_rcp_f32_e32 v78, v78
	v_rcp_f32_e32 v148, v148
	v_mul_f32_e32 v82, v76, v82
	v_mul_f32_e32 v83, v77, v83
	v_mul_f32_e32 v84, v78, v84
	v_mul_f32_e32 v85, v148, v85
	v_mul_f32_e32 v50, v50, v82
	v_mul_f32_e32 v34, v34, v83
	v_mul_f32_e32 v18, v18, v84
	v_mul_f32_e32 v2, v2, v85
	v_cvt_pk_bf16_f32 v50, v50, v149
	v_cvt_pk_bf16_f32 v34, v34, v149
	v_cvt_pk_bf16_f32 v18, v18, v149
	v_cvt_pk_bf16_f32 v2, v2, v149
	ds_write_b16 v74, v50
	ds_write_b16 v74, v34 offset:64
	ds_write_b16 v74, v18 offset:128
	ds_write_b16 v74, v2 offset:192
	v_lshlrev_b32_e32 v86, 16, v86
	v_lshlrev_b32_e32 v87, 16, v87
	v_lshlrev_b32_e32 v88, 16, v88
	v_lshlrev_b32_e32 v89, 16, v89
	v_mul_f32_e32 v76, 0xbfb8aa3b, v86
	v_mul_f32_e32 v77, 0xbfb8aa3b, v87
	v_mul_f32_e32 v78, 0xbfb8aa3b, v88
	v_mul_f32_e32 v148, 0xbfb8aa3b, v89
	v_exp_f32_e32 v76, v76
	v_exp_f32_e32 v77, v77
	v_exp_f32_e32 v78, v78
	v_exp_f32_e32 v148, v148
	v_add_f32_e32 v76, 1.0, v76
	v_add_f32_e32 v77, 1.0, v77
	v_add_f32_e32 v78, 1.0, v78
	v_add_f32_e32 v148, 1.0, v148
	v_rcp_f32_e32 v76, v76
	v_rcp_f32_e32 v77, v77
	v_rcp_f32_e32 v78, v78
	v_rcp_f32_e32 v148, v148
	v_mul_f32_e32 v86, v76, v86
	v_mul_f32_e32 v87, v77, v87
	v_mul_f32_e32 v88, v78, v88
	v_mul_f32_e32 v89, v148, v89
	v_mul_f32_e32 v51, v51, v86
	v_mul_f32_e32 v35, v35, v87
	v_mul_f32_e32 v19, v19, v88
	v_mul_f32_e32 v3, v3, v89
	v_cvt_pk_bf16_f32 v51, v51, v149
	v_cvt_pk_bf16_f32 v35, v35, v149
	v_cvt_pk_bf16_f32 v19, v19, v149
	v_cvt_pk_bf16_f32 v3, v3, v149
	ds_write_b16 v74, v51 offset:272
	ds_write_b16 v74, v35 offset:336
	ds_write_b16 v74, v19 offset:400
	ds_write_b16 v74, v3 offset:464
	v_lshlrev_b32_e32 v90, 16, v90
	v_lshlrev_b32_e32 v91, 16, v91
	v_lshlrev_b32_e32 v92, 16, v92
	v_lshlrev_b32_e32 v93, 16, v93
	v_mul_f32_e32 v76, 0xbfb8aa3b, v90
	v_mul_f32_e32 v77, 0xbfb8aa3b, v91
	v_mul_f32_e32 v78, 0xbfb8aa3b, v92
	v_mul_f32_e32 v148, 0xbfb8aa3b, v93
	v_exp_f32_e32 v76, v76
	v_exp_f32_e32 v77, v77
	v_exp_f32_e32 v78, v78
	v_exp_f32_e32 v148, v148
	v_add_f32_e32 v76, 1.0, v76
	v_add_f32_e32 v77, 1.0, v77
	v_add_f32_e32 v78, 1.0, v78
	v_add_f32_e32 v148, 1.0, v148
	v_rcp_f32_e32 v76, v76
	v_rcp_f32_e32 v77, v77
	v_rcp_f32_e32 v78, v78
	v_rcp_f32_e32 v148, v148
	v_mul_f32_e32 v90, v76, v90
	v_mul_f32_e32 v91, v77, v91
	v_mul_f32_e32 v92, v78, v92
	v_mul_f32_e32 v93, v148, v93
	v_mul_f32_e32 v52, v52, v90
	v_mul_f32_e32 v36, v36, v91
	v_mul_f32_e32 v20, v20, v92
	v_mul_f32_e32 v4, v4, v93
	v_cvt_pk_bf16_f32 v52, v52, v149
	v_cvt_pk_bf16_f32 v36, v36, v149
	v_cvt_pk_bf16_f32 v20, v20, v149
	v_cvt_pk_bf16_f32 v4, v4, v149
	ds_write_b16 v74, v52 offset:544
	ds_write_b16 v74, v36 offset:608
	ds_write_b16 v74, v20 offset:672
	ds_write_b16 v74, v4 offset:736
	v_lshlrev_b32_e32 v94, 16, v94
	v_lshlrev_b32_e32 v95, 16, v95
	v_lshlrev_b32_e32 v96, 16, v96
	v_lshlrev_b32_e32 v97, 16, v97
	v_mul_f32_e32 v76, 0xbfb8aa3b, v94
	v_mul_f32_e32 v77, 0xbfb8aa3b, v95
	v_mul_f32_e32 v78, 0xbfb8aa3b, v96
	v_mul_f32_e32 v148, 0xbfb8aa3b, v97
	v_exp_f32_e32 v76, v76
	v_exp_f32_e32 v77, v77
	v_exp_f32_e32 v78, v78
	v_exp_f32_e32 v148, v148
	v_add_f32_e32 v76, 1.0, v76
	v_add_f32_e32 v77, 1.0, v77
	v_add_f32_e32 v78, 1.0, v78
	v_add_f32_e32 v148, 1.0, v148
	v_rcp_f32_e32 v76, v76
	v_rcp_f32_e32 v77, v77
	v_rcp_f32_e32 v78, v78
	v_rcp_f32_e32 v148, v148
	v_mul_f32_e32 v94, v76, v94
	v_mul_f32_e32 v95, v77, v95
	v_mul_f32_e32 v96, v78, v96
	v_mul_f32_e32 v97, v148, v97
	v_mul_f32_e32 v53, v53, v94
	v_mul_f32_e32 v37, v37, v95
	v_mul_f32_e32 v21, v21, v96
	v_mul_f32_e32 v5, v5, v97
	v_cvt_pk_bf16_f32 v53, v53, v149
	v_cvt_pk_bf16_f32 v37, v37, v149
	v_cvt_pk_bf16_f32 v21, v21, v149
	v_cvt_pk_bf16_f32 v5, v5, v149
	ds_write_b16 v74, v53 offset:816
	ds_write_b16 v74, v37 offset:880
	ds_write_b16 v74, v21 offset:944
	ds_write_b16 v74, v5 offset:1008
	v_lshlrev_b32_e32 v98, 16, v98
	v_lshlrev_b32_e32 v99, 16, v99
	v_lshlrev_b32_e32 v100, 16, v100
	v_lshlrev_b32_e32 v101, 16, v101
	v_mul_f32_e32 v76, 0xbfb8aa3b, v98
	v_mul_f32_e32 v77, 0xbfb8aa3b, v99
	v_mul_f32_e32 v78, 0xbfb8aa3b, v100
	v_mul_f32_e32 v148, 0xbfb8aa3b, v101
	v_exp_f32_e32 v76, v76
	v_exp_f32_e32 v77, v77
	v_exp_f32_e32 v78, v78
	v_exp_f32_e32 v148, v148
	v_add_f32_e32 v76, 1.0, v76
	v_add_f32_e32 v77, 1.0, v77
	v_add_f32_e32 v78, 1.0, v78
	v_add_f32_e32 v148, 1.0, v148
	v_rcp_f32_e32 v76, v76
	v_rcp_f32_e32 v77, v77
	v_rcp_f32_e32 v78, v78
	v_rcp_f32_e32 v148, v148
	v_mul_f32_e32 v98, v76, v98
	v_mul_f32_e32 v99, v77, v99
	v_mul_f32_e32 v100, v78, v100
	v_mul_f32_e32 v101, v148, v101
	v_mul_f32_e32 v54, v54, v98
	v_mul_f32_e32 v38, v38, v99
	v_mul_f32_e32 v22, v22, v100
	v_mul_f32_e32 v6, v6, v101
	v_cvt_pk_bf16_f32 v54, v54, v149
	v_cvt_pk_bf16_f32 v38, v38, v149
	v_cvt_pk_bf16_f32 v22, v22, v149
	v_cvt_pk_bf16_f32 v6, v6, v149
	ds_write_b16 v74, v54 offset:2176
	ds_write_b16 v74, v38 offset:2240
	ds_write_b16 v74, v22 offset:2304
	ds_write_b16 v74, v6 offset:2368
	v_lshlrev_b32_e32 v102, 16, v102
	v_lshlrev_b32_e32 v103, 16, v103
	v_lshlrev_b32_e32 v104, 16, v104
	v_lshlrev_b32_e32 v105, 16, v105
	v_mul_f32_e32 v76, 0xbfb8aa3b, v102
	v_mul_f32_e32 v77, 0xbfb8aa3b, v103
	v_mul_f32_e32 v78, 0xbfb8aa3b, v104
	v_mul_f32_e32 v148, 0xbfb8aa3b, v105
	v_exp_f32_e32 v76, v76
	v_exp_f32_e32 v77, v77
	v_exp_f32_e32 v78, v78
	v_exp_f32_e32 v148, v148
	v_add_f32_e32 v76, 1.0, v76
	v_add_f32_e32 v77, 1.0, v77
	v_add_f32_e32 v78, 1.0, v78
	v_add_f32_e32 v148, 1.0, v148
	v_rcp_f32_e32 v76, v76
	v_rcp_f32_e32 v77, v77
	v_rcp_f32_e32 v78, v78
	v_rcp_f32_e32 v148, v148
	v_mul_f32_e32 v102, v76, v102
	v_mul_f32_e32 v103, v77, v103
	v_mul_f32_e32 v104, v78, v104
	v_mul_f32_e32 v105, v148, v105
	v_mul_f32_e32 v55, v55, v102
	v_mul_f32_e32 v39, v39, v103
	v_mul_f32_e32 v23, v23, v104
	v_mul_f32_e32 v7, v7, v105
	v_cvt_pk_bf16_f32 v55, v55, v149
	v_cvt_pk_bf16_f32 v39, v39, v149
	v_cvt_pk_bf16_f32 v23, v23, v149
	v_cvt_pk_bf16_f32 v7, v7, v149
	ds_write_b16 v74, v55 offset:2448
	ds_write_b16 v74, v39 offset:2512
	ds_write_b16 v74, v23 offset:2576
	ds_write_b16 v74, v7 offset:2640
	v_lshlrev_b32_e32 v106, 16, v106
	v_lshlrev_b32_e32 v107, 16, v107
	v_lshlrev_b32_e32 v108, 16, v108
	v_lshlrev_b32_e32 v109, 16, v109
	v_mul_f32_e32 v76, 0xbfb8aa3b, v106
	v_mul_f32_e32 v77, 0xbfb8aa3b, v107
	v_mul_f32_e32 v78, 0xbfb8aa3b, v108
	v_mul_f32_e32 v148, 0xbfb8aa3b, v109
	v_exp_f32_e32 v76, v76
	v_exp_f32_e32 v77, v77
	v_exp_f32_e32 v78, v78
	v_exp_f32_e32 v148, v148
	v_add_f32_e32 v76, 1.0, v76
	v_add_f32_e32 v77, 1.0, v77
	v_add_f32_e32 v78, 1.0, v78
	v_add_f32_e32 v148, 1.0, v148
	v_rcp_f32_e32 v76, v76
	v_rcp_f32_e32 v77, v77
	v_rcp_f32_e32 v78, v78
	v_rcp_f32_e32 v148, v148
	v_mul_f32_e32 v106, v76, v106
	v_mul_f32_e32 v107, v77, v107
	v_mul_f32_e32 v108, v78, v108
	v_mul_f32_e32 v109, v148, v109
	v_mul_f32_e32 v56, v56, v106
	v_mul_f32_e32 v40, v40, v107
	v_mul_f32_e32 v24, v24, v108
	v_mul_f32_e32 v8, v8, v109
	v_cvt_pk_bf16_f32 v56, v56, v149
	v_cvt_pk_bf16_f32 v40, v40, v149
	v_cvt_pk_bf16_f32 v24, v24, v149
	v_cvt_pk_bf16_f32 v8, v8, v149
	ds_write_b16 v74, v56 offset:2720
	ds_write_b16 v74, v40 offset:2784
	ds_write_b16 v74, v24 offset:2848
	ds_write_b16 v74, v8 offset:2912
	v_lshlrev_b32_e32 v110, 16, v110
	v_lshlrev_b32_e32 v111, 16, v111
	v_lshlrev_b32_e32 v112, 16, v112
	v_lshlrev_b32_e32 v113, 16, v113
	v_mul_f32_e32 v76, 0xbfb8aa3b, v110
	v_mul_f32_e32 v77, 0xbfb8aa3b, v111
	v_mul_f32_e32 v78, 0xbfb8aa3b, v112
	v_mul_f32_e32 v148, 0xbfb8aa3b, v113
	v_exp_f32_e32 v76, v76
	v_exp_f32_e32 v77, v77
	v_exp_f32_e32 v78, v78
	v_exp_f32_e32 v148, v148
	v_add_f32_e32 v76, 1.0, v76
	v_add_f32_e32 v77, 1.0, v77
	v_add_f32_e32 v78, 1.0, v78
	v_add_f32_e32 v148, 1.0, v148
	v_rcp_f32_e32 v76, v76
	v_rcp_f32_e32 v77, v77
	v_rcp_f32_e32 v78, v78
	v_rcp_f32_e32 v148, v148
	v_mul_f32_e32 v110, v76, v110
	v_mul_f32_e32 v111, v77, v111
	v_mul_f32_e32 v112, v78, v112
	v_mul_f32_e32 v113, v148, v113
	v_mul_f32_e32 v57, v57, v110
	v_mul_f32_e32 v41, v41, v111
	v_mul_f32_e32 v25, v25, v112
	v_mul_f32_e32 v9, v9, v113
	v_cvt_pk_bf16_f32 v57, v57, v149
	v_cvt_pk_bf16_f32 v41, v41, v149
	v_cvt_pk_bf16_f32 v25, v25, v149
	v_cvt_pk_bf16_f32 v9, v9, v149
	ds_write_b16 v74, v57 offset:2992
	ds_write_b16 v74, v41 offset:3056
	ds_write_b16 v74, v25 offset:3120
	ds_write_b16 v74, v9 offset:3184
	v_lshlrev_b32_e32 v114, 16, v114
	v_lshlrev_b32_e32 v115, 16, v115
	v_lshlrev_b32_e32 v116, 16, v116
	v_lshlrev_b32_e32 v117, 16, v117
	v_mul_f32_e32 v76, 0xbfb8aa3b, v114
	v_mul_f32_e32 v77, 0xbfb8aa3b, v115
	v_mul_f32_e32 v78, 0xbfb8aa3b, v116
	v_mul_f32_e32 v148, 0xbfb8aa3b, v117
	v_exp_f32_e32 v76, v76
	v_exp_f32_e32 v77, v77
	v_exp_f32_e32 v78, v78
	v_exp_f32_e32 v148, v148
	v_add_f32_e32 v76, 1.0, v76
	v_add_f32_e32 v77, 1.0, v77
	v_add_f32_e32 v78, 1.0, v78
	v_add_f32_e32 v148, 1.0, v148
	v_rcp_f32_e32 v76, v76
	v_rcp_f32_e32 v77, v77
	v_rcp_f32_e32 v78, v78
	v_rcp_f32_e32 v148, v148
	v_mul_f32_e32 v114, v76, v114
	v_mul_f32_e32 v115, v77, v115
	v_mul_f32_e32 v116, v78, v116
	v_mul_f32_e32 v117, v148, v117
	v_mul_f32_e32 v58, v58, v114
	v_mul_f32_e32 v42, v42, v115
	v_mul_f32_e32 v26, v26, v116
	v_mul_f32_e32 v10, v10, v117
	v_cvt_pk_bf16_f32 v58, v58, v149
	v_cvt_pk_bf16_f32 v42, v42, v149
	v_cvt_pk_bf16_f32 v26, v26, v149
	v_cvt_pk_bf16_f32 v10, v10, v149
	ds_write_b16 v74, v58 offset:4352
	ds_write_b16 v74, v42 offset:4416
	ds_write_b16 v74, v26 offset:4480
	ds_write_b16 v74, v10 offset:4544
	v_lshlrev_b32_e32 v118, 16, v118
	v_lshlrev_b32_e32 v119, 16, v119
	v_lshlrev_b32_e32 v120, 16, v120
	v_lshlrev_b32_e32 v121, 16, v121
	v_mul_f32_e32 v76, 0xbfb8aa3b, v118
	v_mul_f32_e32 v77, 0xbfb8aa3b, v119
	v_mul_f32_e32 v78, 0xbfb8aa3b, v120
	v_mul_f32_e32 v148, 0xbfb8aa3b, v121
	v_exp_f32_e32 v76, v76
	v_exp_f32_e32 v77, v77
	v_exp_f32_e32 v78, v78
	v_exp_f32_e32 v148, v148
	v_add_f32_e32 v76, 1.0, v76
	v_add_f32_e32 v77, 1.0, v77
	v_add_f32_e32 v78, 1.0, v78
	v_add_f32_e32 v148, 1.0, v148
	v_rcp_f32_e32 v76, v76
	v_rcp_f32_e32 v77, v77
	v_rcp_f32_e32 v78, v78
	v_rcp_f32_e32 v148, v148
	v_mul_f32_e32 v118, v76, v118
	v_mul_f32_e32 v119, v77, v119
	v_mul_f32_e32 v120, v78, v120
	v_mul_f32_e32 v121, v148, v121
	v_mul_f32_e32 v59, v59, v118
	v_mul_f32_e32 v43, v43, v119
	v_mul_f32_e32 v27, v27, v120
	v_mul_f32_e32 v11, v11, v121
	v_cvt_pk_bf16_f32 v59, v59, v149
	v_cvt_pk_bf16_f32 v43, v43, v149
	v_cvt_pk_bf16_f32 v27, v27, v149
	v_cvt_pk_bf16_f32 v11, v11, v149
	ds_write_b16 v74, v59 offset:4624
	ds_write_b16 v74, v43 offset:4688
	ds_write_b16 v74, v27 offset:4752
	ds_write_b16 v74, v11 offset:4816
	v_lshlrev_b32_e32 v122, 16, v122
	v_lshlrev_b32_e32 v123, 16, v123
	v_lshlrev_b32_e32 v124, 16, v124
	v_lshlrev_b32_e32 v125, 16, v125
	v_mul_f32_e32 v76, 0xbfb8aa3b, v122
	v_mul_f32_e32 v77, 0xbfb8aa3b, v123
	v_mul_f32_e32 v78, 0xbfb8aa3b, v124
	v_mul_f32_e32 v148, 0xbfb8aa3b, v125
	v_exp_f32_e32 v76, v76
	v_exp_f32_e32 v77, v77
	v_exp_f32_e32 v78, v78
	v_exp_f32_e32 v148, v148
	v_add_f32_e32 v76, 1.0, v76
	v_add_f32_e32 v77, 1.0, v77
	v_add_f32_e32 v78, 1.0, v78
	v_add_f32_e32 v148, 1.0, v148
	v_rcp_f32_e32 v76, v76
	v_rcp_f32_e32 v77, v77
	v_rcp_f32_e32 v78, v78
	v_rcp_f32_e32 v148, v148
	v_mul_f32_e32 v122, v76, v122
	v_mul_f32_e32 v123, v77, v123
	v_mul_f32_e32 v124, v78, v124
	v_mul_f32_e32 v125, v148, v125
	v_mul_f32_e32 v60, v60, v122
	v_mul_f32_e32 v44, v44, v123
	v_mul_f32_e32 v28, v28, v124
	v_mul_f32_e32 v12, v12, v125
	v_cvt_pk_bf16_f32 v60, v60, v149
	v_cvt_pk_bf16_f32 v44, v44, v149
	v_cvt_pk_bf16_f32 v28, v28, v149
	v_cvt_pk_bf16_f32 v12, v12, v149
	ds_write_b16 v74, v60 offset:4896
	ds_write_b16 v74, v44 offset:4960
	ds_write_b16 v74, v28 offset:5024
	ds_write_b16 v74, v12 offset:5088
	v_lshlrev_b32_e32 v126, 16, v126
	v_lshlrev_b32_e32 v127, 16, v127
	v_lshlrev_b32_e32 v128, 16, v128
	v_lshlrev_b32_e32 v129, 16, v129
	v_mul_f32_e32 v76, 0xbfb8aa3b, v126
	v_mul_f32_e32 v77, 0xbfb8aa3b, v127
	v_mul_f32_e32 v78, 0xbfb8aa3b, v128
	v_mul_f32_e32 v148, 0xbfb8aa3b, v129
	v_exp_f32_e32 v76, v76
	v_exp_f32_e32 v77, v77
	v_exp_f32_e32 v78, v78
	v_exp_f32_e32 v148, v148
	v_add_f32_e32 v76, 1.0, v76
	v_add_f32_e32 v77, 1.0, v77
	v_add_f32_e32 v78, 1.0, v78
	v_add_f32_e32 v148, 1.0, v148
	v_rcp_f32_e32 v76, v76
	v_rcp_f32_e32 v77, v77
	v_rcp_f32_e32 v78, v78
	v_rcp_f32_e32 v148, v148
	v_mul_f32_e32 v126, v76, v126
	v_mul_f32_e32 v127, v77, v127
	v_mul_f32_e32 v128, v78, v128
	v_mul_f32_e32 v129, v148, v129
	v_mul_f32_e32 v61, v61, v126
	v_mul_f32_e32 v45, v45, v127
	v_mul_f32_e32 v29, v29, v128
	v_mul_f32_e32 v13, v13, v129
	v_cvt_pk_bf16_f32 v61, v61, v149
	v_cvt_pk_bf16_f32 v45, v45, v149
	v_cvt_pk_bf16_f32 v29, v29, v149
	v_cvt_pk_bf16_f32 v13, v13, v149
	ds_write_b16 v74, v61 offset:5168
	ds_write_b16 v74, v45 offset:5232
	ds_write_b16 v74, v29 offset:5296
	ds_write_b16 v74, v13 offset:5360
	v_lshlrev_b32_e32 v130, 16, v130
	v_lshlrev_b32_e32 v131, 16, v131
	v_lshlrev_b32_e32 v132, 16, v132
	v_lshlrev_b32_e32 v133, 16, v133
	v_mul_f32_e32 v76, 0xbfb8aa3b, v130
	v_mul_f32_e32 v77, 0xbfb8aa3b, v131
	v_mul_f32_e32 v78, 0xbfb8aa3b, v132
	v_mul_f32_e32 v148, 0xbfb8aa3b, v133
	v_exp_f32_e32 v76, v76
	v_exp_f32_e32 v77, v77
	v_exp_f32_e32 v78, v78
	v_exp_f32_e32 v148, v148
	v_add_f32_e32 v76, 1.0, v76
	v_add_f32_e32 v77, 1.0, v77
	v_add_f32_e32 v78, 1.0, v78
	v_add_f32_e32 v148, 1.0, v148
	v_rcp_f32_e32 v76, v76
	v_rcp_f32_e32 v77, v77
	v_rcp_f32_e32 v78, v78
	v_rcp_f32_e32 v148, v148
	v_mul_f32_e32 v130, v76, v130
	v_mul_f32_e32 v131, v77, v131
	v_mul_f32_e32 v132, v78, v132
	v_mul_f32_e32 v133, v148, v133
	v_mul_f32_e32 v62, v62, v130
	v_mul_f32_e32 v46, v46, v131
	v_mul_f32_e32 v30, v30, v132
	v_mul_f32_e32 v14, v14, v133
	v_cvt_pk_bf16_f32 v62, v62, v149
	v_cvt_pk_bf16_f32 v46, v46, v149
	v_cvt_pk_bf16_f32 v30, v30, v149
	v_cvt_pk_bf16_f32 v14, v14, v149
	ds_write_b16 v74, v62 offset:6528
	ds_write_b16 v74, v46 offset:6592
	ds_write_b16 v74, v30 offset:6656
	ds_write_b16 v74, v14 offset:6720
	v_lshlrev_b32_e32 v134, 16, v134
	v_lshlrev_b32_e32 v135, 16, v135
	v_lshlrev_b32_e32 v136, 16, v136
	v_lshlrev_b32_e32 v137, 16, v137
	v_mul_f32_e32 v76, 0xbfb8aa3b, v134
	v_mul_f32_e32 v77, 0xbfb8aa3b, v135
	v_mul_f32_e32 v78, 0xbfb8aa3b, v136
	v_mul_f32_e32 v148, 0xbfb8aa3b, v137
	v_exp_f32_e32 v76, v76
	v_exp_f32_e32 v77, v77
	v_exp_f32_e32 v78, v78
	v_exp_f32_e32 v148, v148
	v_add_f32_e32 v76, 1.0, v76
	v_add_f32_e32 v77, 1.0, v77
	v_add_f32_e32 v78, 1.0, v78
	v_add_f32_e32 v148, 1.0, v148
	v_rcp_f32_e32 v76, v76
	v_rcp_f32_e32 v77, v77
	v_rcp_f32_e32 v78, v78
	v_rcp_f32_e32 v148, v148
	v_mul_f32_e32 v134, v76, v134
	v_mul_f32_e32 v135, v77, v135
	v_mul_f32_e32 v136, v78, v136
	v_mul_f32_e32 v137, v148, v137
	v_mul_f32_e32 v63, v63, v134
	v_mul_f32_e32 v47, v47, v135
	v_mul_f32_e32 v31, v31, v136
	v_mul_f32_e32 v15, v15, v137
	v_cvt_pk_bf16_f32 v63, v63, v149
	v_cvt_pk_bf16_f32 v47, v47, v149
	v_cvt_pk_bf16_f32 v31, v31, v149
	v_cvt_pk_bf16_f32 v15, v15, v149
	ds_write_b16 v74, v63 offset:6800
	ds_write_b16 v74, v47 offset:6864
	ds_write_b16 v74, v31 offset:6928
	ds_write_b16 v74, v15 offset:6992
	v_lshlrev_b32_e32 v138, 16, v138
	v_lshlrev_b32_e32 v139, 16, v139
	v_lshlrev_b32_e32 v140, 16, v140
	v_lshlrev_b32_e32 v141, 16, v141
	v_mul_f32_e32 v76, 0xbfb8aa3b, v138
	v_mul_f32_e32 v77, 0xbfb8aa3b, v139
	v_mul_f32_e32 v78, 0xbfb8aa3b, v140
	v_mul_f32_e32 v148, 0xbfb8aa3b, v141
	v_exp_f32_e32 v76, v76
	v_exp_f32_e32 v77, v77
	v_exp_f32_e32 v78, v78
	v_exp_f32_e32 v148, v148
	v_add_f32_e32 v76, 1.0, v76
	v_add_f32_e32 v77, 1.0, v77
	v_add_f32_e32 v78, 1.0, v78
	v_add_f32_e32 v148, 1.0, v148
	v_rcp_f32_e32 v76, v76
	v_rcp_f32_e32 v77, v77
	v_rcp_f32_e32 v78, v78
	v_rcp_f32_e32 v148, v148
	v_mul_f32_e32 v138, v76, v138
	v_mul_f32_e32 v139, v77, v139
	v_mul_f32_e32 v140, v78, v140
	v_mul_f32_e32 v141, v148, v141
	v_mul_f32_e32 v64, v64, v138
	v_mul_f32_e32 v48, v48, v139
	v_mul_f32_e32 v32, v32, v140
	v_mul_f32_e32 v16, v16, v141
	v_cvt_pk_bf16_f32 v64, v64, v149
	v_cvt_pk_bf16_f32 v48, v48, v149
	v_cvt_pk_bf16_f32 v32, v32, v149
	v_cvt_pk_bf16_f32 v16, v16, v149
	ds_write_b16 v74, v64 offset:7072
	ds_write_b16 v74, v48 offset:7136
	ds_write_b16 v74, v32 offset:7200
	ds_write_b16 v74, v16 offset:7264
	v_lshlrev_b32_e32 v142, 16, v142
	v_lshlrev_b32_e32 v143, 16, v143
	v_lshlrev_b32_e32 v144, 16, v144
	v_lshlrev_b32_e32 v145, 16, v145
	v_mul_f32_e32 v76, 0xbfb8aa3b, v142
	v_mul_f32_e32 v77, 0xbfb8aa3b, v143
	v_mul_f32_e32 v78, 0xbfb8aa3b, v144
	v_mul_f32_e32 v148, 0xbfb8aa3b, v145
	v_exp_f32_e32 v76, v76
	v_exp_f32_e32 v77, v77
	v_exp_f32_e32 v78, v78
	v_exp_f32_e32 v148, v148
	v_add_f32_e32 v76, 1.0, v76
	v_add_f32_e32 v77, 1.0, v77
	v_add_f32_e32 v78, 1.0, v78
	v_add_f32_e32 v148, 1.0, v148
	v_rcp_f32_e32 v76, v76
	v_rcp_f32_e32 v77, v77
	v_rcp_f32_e32 v78, v78
	v_rcp_f32_e32 v148, v148
	v_mul_f32_e32 v142, v76, v142
	v_mul_f32_e32 v143, v77, v143
	v_mul_f32_e32 v144, v78, v144
	v_mul_f32_e32 v145, v148, v145
	v_mul_f32_e32 v65, v65, v142
	v_mul_f32_e32 v49, v49, v143
	v_mul_f32_e32 v33, v33, v144
	v_mul_f32_e32 v17, v17, v145
	v_cvt_pk_bf16_f32 v65, v65, v149
	v_cvt_pk_bf16_f32 v49, v49, v149
	v_cvt_pk_bf16_f32 v33, v33, v149
	v_cvt_pk_bf16_f32 v17, v17, v149
	ds_write_b16 v74, v65 offset:7344
	ds_write_b16 v74, v49 offset:7408
	ds_write_b16 v74, v33 offset:7472
	ds_write_b16 v74, v17 offset:7536
	s_waitcnt lgkmcnt(0)
	ds_read_b128 v[82:85], v75
	ds_read_b128 v[86:89], v75 offset:1088
	ds_read_b128 v[90:93], v75 offset:2176
	ds_read_b128 v[94:97], v75 offset:3264
	ds_read_b128 v[98:101], v75 offset:4352
	ds_read_b128 v[102:105], v75 offset:5440
	ds_read_b128 v[106:109], v75 offset:6528
	ds_read_b128 v[110:113], v75 offset:7616
	s_waitcnt lgkmcnt(0)
	global_store_dwordx4 v73, v[82:85], s[12:13]
	v_add_u32_e32 v73, 0x4000, v73
	global_store_dwordx4 v73, v[86:89], s[12:13]
	v_add_u32_e32 v73, 0x4000, v73
	global_store_dwordx4 v73, v[90:93], s[12:13]
	v_add_u32_e32 v73, 0x4000, v73
	global_store_dwordx4 v73, v[94:97], s[12:13]
	v_add_u32_e32 v73, 0x4000, v73
	global_store_dwordx4 v73, v[98:101], s[12:13]
	v_add_u32_e32 v73, 0x4000, v73
	global_store_dwordx4 v73, v[102:105], s[12:13]
	v_add_u32_e32 v73, 0x4000, v73
	global_store_dwordx4 v73, v[106:109], s[12:13]
	v_add_u32_e32 v73, 0x4000, v73
	global_store_dwordx4 v73, v[110:113], s[12:13]
	s_and_b64 vcc, exec, s[88:89]
	s_mov_b64 s[8:9], 0
	s_waitcnt lgkmcnt(0)
	s_barrier
	s_cbranch_vccnz .LBB0_297
